# move Fdn1 weight conversion from G1 idle-CU tail to G3_1 idle-CU tail
# speedup vs baseline: 1.0937x; 1.0937x over previous
.LBB0_499:
	v_readlane_b32 s8, v247, 59
	v_readlane_b32 s14, v246, 1
	s_cmp_lt_i32 s14, 7
	v_readlane_b32 s92, v246, 61
	v_readlane_b32 s34, v246, 63
	v_readlane_b32 s2, v247, 39
	s_mov_b32 s22, 0x80000
	v_readlane_b32 s9, v247, 60
	v_readlane_b32 s10, v247, 61
	v_readlane_b32 s11, v247, 62
	v_readlane_b32 s12, v247, 63
	v_readlane_b32 s13, v246, 0
	v_readlane_b32 s15, v246, 2
	v_readlane_b32 s93, v246, 62
	v_readlane_b32 s35, v245, 0
	v_readlane_b32 s3, v247, 40
	s_cbranch_scc1 .LBB0_502
	s_cmp_gt_i32 s14, 10
	s_mov_b32 s23, 0x60000
	s_mov_b32 s30, 0x160000
	s_mov_b32 s31, 0x1a0000
	s_mov_b32 s35, 0x1c0000
	s_mov_b32 s93, 0x1e0000
	s_mov_b32 s26, 0x210000
	s_cbranch_scc0 .LBB0_503
	s_cmp_eq_u32 s14, 11
	s_cselect_b64 s[0:1], -1, 0
	s_cmp_eq_u32 s14, 16
	s_cselect_b64 s[0:1], -1, s[0:1]
	s_cbranch_execz .LBB0_504
	s_branch .LBB0_505

.LBB0_507:
	s_andn2_b64 vcc, exec, s[0:1]
	s_cbranch_vccnz .LBB0_576
	v_readlane_b32 s0, v247, 26
	s_mul_hi_u32 s0, s6, s0
	v_readlane_b32 s2, v247, 25
	s_mul_i32 s0, s0, s2
	s_sub_i32 s0, s6, s0
	s_sub_i32 s1, s0, s2
	s_cmp_ge_u32 s0, s2
	s_cselect_b32 s0, s1, s0
	s_sub_i32 s1, s0, s2
	s_cmp_ge_u32 s0, s2
	s_cselect_b32 s10, s1, s0
	s_cmp_lg_u32 s10, 0
	v_readlane_b32 s2, v246, 59
	s_cselect_b64 s[0:1], -1, 0
	v_readlane_b32 s3, v246, 60
	s_cmp_lt_i32 s2, s10
	s_cselect_b64 s[2:3], -1, 0
	s_and_b64 s[0:1], s[0:1], s[2:3]
	s_and_b64 vcc, exec, s[0:1]
	s_mov_b32 s84, 0xc0000
	s_mov_b32 s27, 0x120000
	s_cbranch_vccnz .LBB0_576
	v_readlane_b32 s0, v246, 59
	v_readlane_b32 s4, v244, 38
	v_readlane_b32 s1, v246, 60
	v_readlane_b32 s5, v244, 39
	s_sub_i32 s3, s0, s10
	s_sub_i32 s2, s36, s10
	s_mov_b64 s[0:1], -1
	s_cmp_eq_u32 s14, 16
	s_cselect_b64 s[4:5], 0, s[4:5]
	s_and_b64 vcc, exec, s[4:5]
	s_cbranch_vccz .LBB0_544
	v_readlane_b32 s76, v247, 59
	v_readlane_b32 s82, v246, 1
	s_cmp_lg_u32 s82, 7
	v_readlane_b32 s77, v247, 60
	v_readlane_b32 s78, v247, 61
	v_readlane_b32 s79, v247, 62
	v_readlane_b32 s80, v247, 63
	v_readlane_b32 s81, v246, 0
	v_readlane_b32 s83, v246, 2
	s_cbranch_scc0 .LBB0_526
	s_lshl_b32 s0, s3, 3
	s_add_i32 s0, s62, s0
	s_add_i32 s11, s0, 0xa00
	s_cmpk_gt_i32 s11, 0x19ff
	s_cbranch_scc1 .LBB0_525
	s_mul_i32 s0, s62, 0x4100
	s_add_i32 s0, s0, 0
	v_lshlrev_b32_e32 v2, 1, v221
	v_mov_b32_e32 v3, s0
	v_lshl_add_u32 v5, v221, 2, s0
	v_lshrrev_b32_e32 v4, 5, v221
	v_and_b32_e32 v0, 62, v2
	s_movk_i32 s0, 0x104
	v_mad_u32_u24 v72, v0, s0, v3
	s_lshl_b32 s12, s2, 3
	v_cmp_gt_u32_e64 s[40:41], 32, v0
	v_mov_b32_e32 v3, v4
	v_lshlrev_b32_e32 v6, 1, v0
	s_branch .LBB0_514

.LBB0_544:
	s_andn2_b64 vcc, exec, s[0:1]
	s_cbranch_vccnz .LBB0_576
	s_lshl_b32 s0, s3, 3
	s_add_i32 s0, s62, s0
	s_movk_i32 s100, 0x4500
	s_movk_i32 s101, 0x5aff
	s_cmp_eq_u32 s14, 16
	s_cbranch_scc0 .Lwc_bounds_done
	s_movk_i32 s100, 0x5b00
	s_movk_i32 s101, 0x65ff
.Lwc_bounds_done:
	s_add_i32 s3, s0, s100
	s_cmp_gt_i32 s3, s101
	s_cbranch_scc1 .LBB0_576
	v_lshlrev_b32_e32 v0, 2, v221
	s_mul_i32 s0, s62, 0x4100
	v_lshrrev_b32_e32 v3, 4, v221
	v_and_b32_e32 v2, 60, v0
	s_add_i32 s0, s0, 0
	v_lshlrev_b32_e32 v0, 2, v2
	v_mul_u32_u24_e32 v4, 0x104, v3
	v_add3_u32 v20, s0, v0, v4
	v_lshlrev_b32_e32 v0, 3, v221
	v_lshrrev_b32_e32 v21, 3, v221
	v_and_b32_e32 v0, 56, v0
	v_mul_u32_u24_e32 v6, 0x104, v0
	v_lshlrev_b32_e32 v7, 2, v21
	v_add3_u32 v22, s0, v6, v7
	v_readlane_b32 s0, v244, 40
	v_lshlrev_b32_e32 v0, 1, v0
	v_readlane_b32 s1, v244, 41
	v_readlane_b32 s4, v244, 42
	v_readlane_b32 s5, v244, 43
	v_lshl_add_u64 v[6:7], s[0:1], 0, v[0:1]
	v_readlane_b32 s0, v245, 50
	v_readlane_b32 s1, v245, 51
	s_lshl_b32 s6, s2, 3
	v_lshl_add_u64 v[4:5], s[4:5], 0, v[0:1]
	v_lshl_add_u64 v[8:9], s[0:1], 0, v[0:1]
	v_readlane_b32 s0, v245, 48
	v_readlane_b32 s1, v245, 49
	v_or_b32_e32 v23, 8, v21
	v_or_b32_e32 v24, 16, v21
	v_lshl_add_u64 v[10:11], s[0:1], 0, v[0:1]
	v_readlane_b32 s0, v245, 46
	v_readlane_b32 s1, v245, 47
	v_or_b32_e32 v25, 24, v21
	v_or_b32_e32 v26, 32, v21
	v_lshl_add_u64 v[12:13], s[0:1], 0, v[0:1]
	v_readlane_b32 s0, v245, 44
	v_readlane_b32 s1, v245, 45
	v_or_b32_e32 v27, 40, v21
	v_or_b32_e32 v28, 48, v21
	v_lshl_add_u64 v[14:15], s[0:1], 0, v[0:1]
	v_readlane_b32 s0, v245, 42
	v_readlane_b32 s1, v245, 43
	v_or_b32_e32 v29, 56, v21
	v_lshl_add_u64 v[18:19], s[16:17], 0, v[0:1]
	v_lshl_add_u64 v[16:17], s[0:1], 0, v[0:1]
	s_lshl_b32 s7, s3, 6
	s_lshl_b32 s8, s2, 9
	s_lshl_b32 s9, s3, 1
	s_lshl_b32 s2, s2, 4
	s_mov_b64 s[12:13], s[90:91]
	s_branch .LBB0_548
.LBB0_547:
	s_add_i32 s3, s3, s6
	s_add_i32 s7, s7, s8
	s_add_i32 s9, s9, s2
	s_cmp_gt_i32 s3, s101
	s_cbranch_scc1 .LBB0_576

	.amdhsa_kernel _Z14fwd_megakernel6Params
		.amdhsa_group_segment_fixed_size 0
		.amdhsa_private_segment_fixed_size 0
		.amdhsa_kernarg_size 448
		.amdhsa_user_sgpr_count 2
		.amdhsa_user_sgpr_dispatch_ptr 0
		.amdhsa_user_sgpr_queue_ptr 0
		.amdhsa_user_sgpr_kernarg_segment_ptr 1
		.amdhsa_user_sgpr_dispatch_id 0
		.amdhsa_user_sgpr_kernarg_preload_length 0
		.amdhsa_user_sgpr_kernarg_preload_offset 0
		.amdhsa_user_sgpr_private_segment_size 0
		.amdhsa_uses_dynamic_stack 0
		.amdhsa_enable_private_segment 0
		.amdhsa_system_sgpr_workgroup_id_x 1
		.amdhsa_system_sgpr_workgroup_id_y 0
		.amdhsa_system_sgpr_workgroup_id_z 0
		.amdhsa_system_sgpr_workgroup_info 0
		.amdhsa_system_vgpr_workitem_id 2
		.amdhsa_next_free_vgpr 249
		.amdhsa_next_free_sgpr 102
		.amdhsa_accum_offset 252
		.amdhsa_reserve_vcc 1
		.amdhsa_float_round_mode_32 0
		.amdhsa_float_round_mode_16_64 0
		.amdhsa_float_denorm_mode_32 3
		.amdhsa_float_denorm_mode_16_64 3
		.amdhsa_dx10_clamp 1
		.amdhsa_ieee_mode 1
		.amdhsa_fp16_overflow 0
		.amdhsa_tg_split 0
		.amdhsa_exception_fp_ieee_invalid_op 0
		.amdhsa_exception_fp_denorm_src 0
		.amdhsa_exception_fp_ieee_div_zero 0
		.amdhsa_exception_fp_ieee_overflow 0
		.amdhsa_exception_fp_ieee_underflow 0
		.amdhsa_exception_fp_ieee_inexact 0
		.amdhsa_exception_int_div_zero 0
	.end_amdhsa_kernel

amdhsa.kernels:
  - .agpr_count:     0
    .args:
      - .offset:         0
        .size:           192
        .value_kind:     by_value
      - .offset:         192
        .size:           4
        .value_kind:     hidden_block_count_x
      - .offset:         196
        .size:           4
        .value_kind:     hidden_block_count_y
      - .offset:         200
        .size:           4
        .value_kind:     hidden_block_count_z
      - .offset:         204
        .size:           2
        .value_kind:     hidden_group_size_x
      - .offset:         206
        .size:           2
        .value_kind:     hidden_group_size_y
      - .offset:         208
        .size:           2
        .value_kind:     hidden_group_size_z
      - .offset:         210
        .size:           2
        .value_kind:     hidden_remainder_x
      - .offset:         212
        .size:           2
        .value_kind:     hidden_remainder_y
      - .offset:         214
        .size:           2
        .value_kind:     hidden_remainder_z
      - .offset:         232
        .size:           8
        .value_kind:     hidden_global_offset_x
      - .offset:         240
        .size:           8
        .value_kind:     hidden_global_offset_y
      - .offset:         248
        .size:           8
        .value_kind:     hidden_global_offset_z
      - .offset:         256
        .size:           2
        .value_kind:     hidden_grid_dims
      - .offset:         280
        .size:           8
        .value_kind:     hidden_multigrid_sync_arg
      - .offset:         312
        .size:           4
        .value_kind:     hidden_dynamic_lds_size
    .group_segment_fixed_size: 0
    .kernarg_segment_align: 8
    .kernarg_segment_size: 448
    .language:       OpenCL C
    .language_version:
      - 2
      - 0
    .max_flat_workgroup_size: 512
    .name:           _Z14fwd_megakernel6Params
    .private_segment_fixed_size: 0
    .sgpr_count:     108
    .sgpr_spill_count: 343
    .symbol:         _Z14fwd_megakernel6Params.kd
    .uniform_work_group_size: 1
    .uses_dynamic_stack: false
    .vgpr_count:     249
    .vgpr_spill_count: 0
    .wavefront_size: 64
